# v036 g5: 192 CUs run 576 tiles in 3 rounds, CUs 192-255 convert w_down[l+1] during the whole phase
# baseline (speedup 1.0000x reference)
;     DEV bool next(int i, Unit& u) const { if (!GroupedOrder::next(i, u)) return false; u.A = A; return true; }
;     DEV bool next(int i, Unit& u) const {
;         const long L = (long)i * G + c; if (L >= nwg) return false;
;         int wgid = (int)L; { const int q = nwg / 8, r = nwg % 8, xcd = wgid % 8, off = wgid / 8; wgid = (xcd < r ? xcd * (q + 1) : r * (q + 1) + (xcd - r) * q) + off; }
;         const int per_e = nMe * nN; const int e = wgid / per_e, w = wgid % per_e;
;         u.e = e; u.pm = w % nMe; u.pn = w / nMe;
;         u.A = A + ((size_t)e * EPAD + (size_t)u.pm * BM) * K * 2; u.B = Bt + (size_t)e * bstride + (size_t)u.pn * BM * K * 2; return true;
; DEV void gemm_g5(const Frame& F0, int l, int vcu) {
;     const Frame F = refresh(F0);
;     pg8::GroupedOrder S; S.init((const void*)(F.ws + WS_HID), (const bf16_t*)(F.ws + WS_WD) + (size_t)l * NE * 1024 * FF, FF, 1024, F.G, vcu, (l == DEPTH - 1) ? B_ * CAPL : EROWS);
;     EpiYse E; E.O = (bf16_t*)(F.ws + WS_YSE); E.rowscale = (const float*)(F.ws + WS_EGATE);
;     pg8::gemm_phase(F.lds, FF, S, E, F.wave, F.lane);
.Lbw11_skip:
	s_waitcnt lgkmcnt(0)
	v_readlane_b32 s38, v255, 61
	s_cmp_lg_u32 s38, 0
	v_readlane_b32 s4, v251, 0
	v_readlane_b32 s6, v251, 2
	v_readlane_b32 s7, v251, 3
	s_lshl_b32 s0, s33, 6
	v_readlane_b32 s10, v251, 29
	v_mov_b32_e32 v16, v200
	s_mov_b64 s[2:3], s[6:7]
	s_cmp_ge_i32 s95, s0
	s_waitcnt lgkmcnt(0)
	s_barrier
	v_readlane_b32 s5, v251, 1
	s_cbranch_scc1 .LBB0_1829
	s_mov_b32 s100, s96
	v_readlane_b32 s101, v255, 52
	s_cmp_gt_u32 s101, 2
	s_cbranch_scc1 .Lg5d_norm
	v_readlane_b32 s101, v255, 51
	s_cmp_lg_u32 s101, 0x100
	s_cbranch_scc1 .Lg5d_norm
	s_movk_i32 s100, 0xc0
	v_readlane_b32 s101, v255, 48
	s_cmp_ge_u32 s101, 0xc0
	s_cbranch_scc1 .Lsd_entry
.Lg5d_norm:
	v_readlane_b32 s4, v253, 62
	s_add_u32 s30, s2, 0x45dd4c00
	v_readlane_b32 s5, v253, 63
	s_addc_u32 s31, s3, 0
	s_lshl_b64 s[4:5], s[4:5], 26
	s_add_u32 s4, s2, s4
	s_addc_u32 s5, s3, s5
	s_add_u32 s34, s4, 0x22bc8000
	s_addc_u32 s35, s5, 0
	s_lshl_b32 s36, s10, 10
	v_lshl_add_u32 v0, v16, 4, s36
	v_add_u32_e32 v2, 0x2000, v0
	v_ashrrev_i32_e32 v3, 31, v2
	v_lshrrev_b32_e32 v3, 22, v3
	v_add_u32_e32 v3, v2, v3
	v_ashrrev_i32_e32 v10, 10, v3
	v_mul_i32_i24_e32 v3, 0x400, v10
	v_sub_u32_e32 v2, v2, v3
	v_lshrrev_b32_e32 v3, 4, v2
	v_bitop3_b32 v2, v3, v2, 32 bitop3:0x6c
	v_ashrrev_i32_e32 v3, 31, v2
	v_lshrrev_b32_e32 v3, 26, v3
	v_add_u32_e32 v3, v2, v3
	v_ashrrev_i32_e32 v11, 6, v3
	v_lshlrev_b32_e32 v4, 3, v10
	v_and_b32_e32 v3, 0xffc0, v3
	v_and_b32_e32 v4, -16, v4
	v_sub_u32_e32 v2, v2, v3
	v_add_u32_e32 v4, v11, v4
	v_lshrrev_b16_e32 v3, 7, v2
	v_and_b32_e32 v5, 3, v11
	s_mov_b32 s4, 0xfffe0
	v_lshrrev_b32_e32 v6, 2, v4
	v_lshlrev_b32_e32 v7, 1, v4
	v_and_b32_e32 v3, 1, v3
	v_and_or_b32 v5, v4, s4, v5
	v_and_b32_e32 v6, 4, v6
	v_and_b32_e32 v7, 24, v7
	v_add_u16_e32 v2, v2, v3
	v_or3_b32 v5, v5, v6, v7
	v_lshlrev_b32_e32 v6, 5, v10
	v_ashrrev_i16_sdwa v2, v202, sext(v2) dst_sel:DWORD dst_unused:UNUSED_PAD src0_sel:DWORD src1_sel:BYTE_0
	v_and_b32_e32 v6, 32, v6
	v_bfe_i32 v13, v2, 0, 16
	v_add_lshl_u32 v2, v6, v13, 1
	v_lshl_add_u32 v130, v5, 12, v2
	v_lshl_add_u32 v132, v4, 12, v2
	v_ashrrev_i32_e32 v2, 31, v0
	v_lshrrev_b32_e32 v2, 22, v2
	v_add_u32_e32 v2, v0, v2
	v_ashrrev_i32_e32 v12, 10, v2
	v_mul_i32_i24_e32 v2, 0x400, v12
	v_sub_u32_e32 v0, v0, v2
	v_lshrrev_b32_e32 v2, 4, v0
	v_bitop3_b32 v0, v2, v0, 32 bitop3:0x6c
	v_ashrrev_i32_e32 v2, 31, v0
	v_lshrrev_b32_e32 v2, 26, v2
	v_add_u32_e32 v2, v0, v2
	v_lshlrev_b32_e32 v3, 3, v12
	v_ashrrev_i32_e32 v14, 6, v2
	v_and_b32_e32 v3, -16, v3
	v_add_u32_e32 v3, v14, v3
	v_and_b32_e32 v4, 3, v14
	v_and_or_b32 v4, v3, s4, v4
	s_lshl_b32 s37, s33, 3
	v_readlane_b32 s4, v252, 24
	s_ashr_i32 s11, s10, 2
	v_lshrrev_b32_e32 v5, 2, v3
	v_lshlrev_b32_e32 v6, 1, v3
	v_and_b32_e32 v2, 0xc0, v2
	s_or_b32 s38, s37, 1
	v_readlane_b32 s5, v252, 25
	v_and_b32_e32 v5, 4, v5
	v_and_b32_e32 v6, 24, v6
	v_sub_u32_e32 v0, v0, v2
	s_and_b64 s[4:5], s[4:5], exec
	v_or3_b32 v4, v4, v5, v6
	v_lshlrev_b32_e32 v5, 5, v12
	v_ashrrev_i16_sdwa v0, v202, sext(v0) dst_sel:DWORD dst_unused:UNUSED_PAD src0_sel:DWORD src1_sel:BYTE_0
	s_cselect_b32 s4, s38, s37
	s_lshl_b32 s39, s33, 2
	v_and_b32_e32 v5, 32, v5
	v_bfe_i32 v15, v0, 0, 16
	s_abs_i32 s40, s39
	v_add_lshl_u32 v2, v5, v15, 1
	v_cvt_f32_u32_e32 v5, s40
	v_lshl_add_u32 v0, v4, 12, v2
	v_lshl_add_u32 v134, v3, 12, v2
	v_readlane_b32 s5, v252, 23
	v_rcp_iflag_f32_e32 v2, v5
	s_sub_i32 s7, 0, s40
	s_mul_i32 s4, s4, s5
	v_readlane_b32 s5, v252, 21
	v_mul_f32_e32 v2, 0x4f7ffffe, v2
	v_cvt_u32_f32_e32 v2, v2
	s_add_i32 s4, s4, s5
	s_abs_i32 s6, s4
	s_ashr_i32 s5, s4, 31
	v_readfirstlane_b32 s42, v2
	s_mul_i32 s7, s7, s42
	s_mul_hi_u32 s7, s42, s7
	s_add_i32 s42, s42, s7
	s_mul_hi_u32 s7, s6, s42
	s_mul_i32 s8, s7, s40
	s_bfe_i32 s41, s33, 0x1001d
	s_sub_i32 s6, s6, s8
	s_xor_b32 s5, s5, s41
	s_add_i32 s8, s7, 1
	s_sub_i32 s9, s6, s40
	s_cmp_ge_u32 s6, s40
	s_cselect_b32 s7, s8, s7
	s_cselect_b32 s6, s9, s6
	s_add_i32 s8, s7, 1
	s_cmp_ge_u32 s6, s40
	s_cselect_b32 s6, s8, s7
	s_xor_b32 s6, s6, s5
	s_sub_i32 s22, s6, s5
	s_sext_i32_i8 s5, s33
	v_cvt_f32_i32_e32 v2, s5
	s_mul_i32 s6, s22, s39
	s_sub_i32 s7, s4, s6
	v_cvt_f32_i32_e32 v3, s7
	v_rcp_iflag_f32_e32 v4, v2
	s_xor_b32 s4, s7, s5
	s_ashr_i32 s4, s4, 30
	s_or_b32 s6, s4, 1
	v_mul_f32_e32 v4, v3, v4
	v_trunc_f32_e32 v4, v4
	v_fma_f32 v3, -v4, v2, v3
	v_cvt_i32_f32_e32 v4, v4
	v_cmp_ge_f32_e64 s[4:5], |v3|, |v2|
	s_and_b64 s[4:5], s[4:5], exec
	s_cselect_b32 s4, s6, 0
	v_readfirstlane_b32 s5, v4
	s_add_i32 s6, s5, s4
	s_mul_i32 s4, s6, s33
	s_sub_i32 s8, s7, s4
	s_bfe_i64 s[4:5], s[8:9], 0x80000
	s_ashr_i32 s23, s22, 31
	s_lshl_b64 s[4:5], s[4:5], 20
	s_add_u32 s4, s30, s4
	s_mul_i32 s9, s22, 0x900000
	s_addc_u32 s5, s31, s5
	s_mul_hi_i32 s7, s22, 0x900000
	s_add_u32 s24, s4, s9
	s_addc_u32 s25, s5, s7
	s_lshl_b64 s[4:5], s[22:23], 22
	s_add_u32 s7, s34, s4
	s_addc_u32 s9, s35, s5
	s_bfe_i64 s[4:5], s[6:7], 0x80000
	s_lshl_b64 s[4:5], s[4:5], 20
	s_add_u32 s26, s7, s4
	s_addc_u32 s27, s9, s5
	s_add_i32 s43, s36, 0
	s_add_i32 m0, s43, 0x10000
	v_add_u32_e32 v136, 0x80000, v134
	global_load_lds_dwordx4 v0, s[26:27]
	s_add_i32 m0, s43, 0x12000
	s_add_u32 s4, s26, 0x80000
	global_load_lds_dwordx4 v130, s[26:27]
	s_addc_u32 s5, s27, 0
	s_add_i32 m0, s43, 0x14000
	s_add_i32 s44, s43, 0x2000
	global_load_lds_dwordx4 v0, s[4:5]
	s_add_i32 m0, s43, 0x16000
	s_add_i32 s45, s43, 0x4000
	global_load_lds_dwordx4 v130, s[4:5]
	s_mov_b32 m0, s43
	s_add_i32 s46, s43, 0x6000
	global_load_lds_dwordx4 v134, s[24:25]
	s_mov_b32 m0, s44
	v_add_u32_e32 v138, 0x80000, v132
	global_load_lds_dwordx4 v132, s[24:25]
	s_mov_b32 m0, s45
	v_mov_b32_e32 v131, v1
	global_load_lds_dwordx4 v136, s[24:25]
	s_mov_b32 m0, s46
	v_mov_b32_e32 v135, v1
	global_load_lds_dwordx4 v138, s[24:25]
	v_mov_b32_e32 v133, v1
	s_cmp_eq_u32 s11, 1
	v_lshl_add_u64 v[8:9], s[26:27], 0, v[0:1]
	v_lshl_add_u64 v[6:7], s[26:27], 0, v[130:131]
	v_lshl_add_u64 v[2:3], s[24:25], 0, v[134:135]
	s_cselect_b64 s[4:5], -1, 0
	s_cmp_lg_u32 s11, 1
	v_lshl_add_u64 v[4:5], s[24:25], 0, v[132:133]
	s_cbranch_scc1 .LBB0_1816
	s_barrier

;     DEV bool next(int i, Unit& u) const { if (!GroupedOrder::next(i, u)) return false; u.A = A; return true; }
;     DEV bool next(int i, Unit& u) const {
;         const long L = (long)i * G + c; if (L >= nwg) return false;
;         int wgid = (int)L; { const int q = nwg / 8, r = nwg % 8, xcd = wgid % 8, off = wgid / 8; wgid = (xcd < r ? xcd * (q + 1) : r * (q + 1) + (xcd - r) * q) + off; }
;         const int per_e = nMe * nN; const int e = wgid / per_e, w = wgid % per_e;
;         u.e = e; u.pm = w % nMe; u.pn = w / nMe;
;         u.A = A + ((size_t)e * EPAD + (size_t)u.pm * BM) * K * 2; u.B = Bt + (size_t)e * bstride + (size_t)u.pn * BM * K * 2; return true;
.LBB0_1819:
	s_add_i32 s51, s51, 1
	s_mul_i32 s2, s51, s83
	s_mul_hi_u32 s3, s51, s100
	s_add_i32 s3, s3, s2
	s_mul_i32 s2, s51, s100
	s_add_u32 s28, s2, s95
	s_addc_u32 s29, s3, s81
	v_mov_b64_e32 v[2:3], s[0:1]
	v_cmp_ge_i64_e32 vcc, s[28:29], v[2:3]
	v_cmp_lt_i64_e64 s[2:3], s[28:29], v[2:3]
	s_cbranch_vccnz .LBB0_1821
	s_ashr_i32 s12, s28, 31
	s_lshr_b32 s12, s12, 29
	s_add_i32 s12, s28, s12
	s_ashr_i32 s13, s12, 3
	s_and_b32 s12, s12, -8
	s_sub_i32 s12, s28, s12
	s_cmp_lt_i32 s12, 0
	s_cselect_b32 s14, s38, s37
	s_mul_i32 s12, s14, s12
	s_add_i32 s13, s12, s13
	s_abs_i32 s14, s13
	s_mul_hi_u32 s15, s14, s42
	s_mul_i32 s16, s15, s40
	s_ashr_i32 s12, s13, 31
	s_sub_i32 s14, s14, s16
	s_xor_b32 s12, s12, s41
	s_add_i32 s16, s15, 1
	s_sub_i32 s17, s14, s40
	s_cmp_ge_u32 s14, s40
	s_cselect_b32 s15, s16, s15
	s_cselect_b32 s14, s17, s14
	s_add_i32 s16, s15, 1
	s_cmp_ge_u32 s14, s40
	s_cselect_b32 s14, s16, s15
	s_xor_b32 s14, s14, s12
	s_sub_i32 s12, s14, s12
	s_mul_i32 s14, s12, s39
	s_sub_i32 s13, s13, s14
	s_abs_i32 s15, s13
	s_mul_hi_u32 s16, s15, s52
	s_mul_i32 s17, s16, s50
	s_ashr_i32 s14, s13, 31
	s_sub_i32 s15, s15, s17
	s_xor_b32 s14, s14, s49
	s_add_i32 s17, s16, 1
	s_sub_i32 s18, s15, s50
	s_cmp_ge_u32 s15, s50
	s_cselect_b32 s16, s17, s16
	s_cselect_b32 s15, s18, s15
	s_add_i32 s17, s16, 1
	s_cmp_ge_u32 s15, s50
	s_cselect_b32 s15, s17, s16
	s_xor_b32 s15, s15, s14
	s_sub_i32 s14, s15, s14
	s_mul_i32 s15, s14, s33
	s_sub_i32 s16, s13, s15
	s_ashr_i32 s17, s16, 31
	s_ashr_i32 s13, s12, 31
	s_lshl_b64 s[18:19], s[16:17], 20
	s_add_u32 s18, s30, s18
	s_mul_i32 s17, s12, 0x900000
	s_addc_u32 s19, s31, s19
	s_mul_hi_i32 s15, s12, 0x900000
	s_add_u32 s18, s18, s17
	s_addc_u32 s19, s19, s15
	s_lshl_b64 s[20:21], s[12:13], 22
	s_add_u32 s13, s34, s20
	s_addc_u32 s17, s35, s21
	s_ashr_i32 s15, s14, 31
	s_lshl_b64 s[20:21], s[14:15], 20
	s_add_u32 s20, s13, s20
	s_addc_u32 s21, s17, s21

; #define WAVE_LDS_SYNC() do { int _z = 0; (void)emu::wave_xchg(&_z, 4); } while (0)
; #define LAS __attribute__((address_space(3)))
; #define WAVE_LDS_SYNC() asm volatile("s_waitcnt lgkmcnt(0)" ::: "memory")
; #define NT_LOAD(p) __builtin_nontemporal_load(p)
; #define NT_STORE(v, p) __builtin_nontemporal_store((v), (p))
; DEV unsigned pk2(float lo, float hi) { return f2bf(lo) | (f2bf(hi) << 16); }
; DEV unsigned pk2(float lo, float hi) { const f32x2n_t v = {lo, hi}; return __builtin_bit_cast(unsigned, __builtin_convertvector(v, bf16x2n_t)); }
; DEV void tr_item(const float* W, int ldw, int col0, int k0, bf16_t* WT, int K, int row0, LAS float* scr, int lane) {
; #pragma unroll 8
;     for (int i = 0; i < 32; ++i) { const int kk = 2 * i + (lane >> 5); scr[kk * 33 + (lane & 31)] = NT_LOAD(&W[(size_t)(k0 + kk) * ldw + col0 + (lane & 31)]); }
;     WAVE_LDS_SYNC();
;     const int c = lane & 7;
; #pragma unroll
;     for (int j = 0; j < 4; ++j) { const int n = (lane >> 3) + 8 * j; const LAS float* s = scr + (8 * c) * 33 + n;
;         u32x4 o; o.x = pk2(s[0 * 33], s[1 * 33]); o.y = pk2(s[2 * 33], s[3 * 33]); o.z = pk2(s[4 * 33], s[5 * 33]); o.w = pk2(s[6 * 33], s[7 * 33]);
;         NT_STORE(o, (u32x4*)(WT + (size_t)(row0 + n) * K + k0 + 8 * c)); }
;     WAVE_LDS_SYNC();
; DEV void phase_prologue_a(const Frame& F0) {
;     ...
;         constexpr int D_ITEMS = (FF / 64) * 32;
;         for (int it = F.gw; it < NE * D_ITEMS; it += F.NGW) { const int e = it / D_ITEMS, r = it % D_ITEMS, kb = r / 32, nb = r % 32;
;             tr_item(GIN(I_WDOWN) + ((size_t)l * NE + e) * FF * 1024, 1024, 32 * nb, 64 * kb, (bf16_t*)(F.ws + WS_WD) + ((size_t)l * NE + e) * 1024 * FF, FF, 32 * nb, scr, F.lane); }
.Lsd_entry:
	v_readlane_b32 s3, v255, 52
	s_add_i32 s0, s3, 1
	v_writelane_b32 v255, s0, 52
	s_cmp_gt_u32 s0, 3
	s_cbranch_scc1 .Lsd_done
	v_readlane_b32 s2, v255, 51
	s_cmp_lg_u32 s2, 0x100
	s_cbranch_scc1 .Lsd_done
	v_readlane_b32 s2, v255, 48
	s_cmp_lt_u32 s2, 0xc0
	s_cbranch_scc1 .Lsd_done
	v_readlane_b32 s3, v251, 29
	s_sub_i32 s2, s2, 0xc0
	s_lshl_b32 s2, s2, 3
	s_add_i32 s2, s2, s3
	v_readlane_b32 s6, v255, 53
	v_readlane_b32 s7, v255, 54
	v_readlane_b32 s4, v255, 49
	v_readlane_b32 s5, v255, 50
	s_add_u32 s6, s6, 0x22bc8000
	s_addc_u32 s7, s7, 0
	s_lshl_b32 s8, s0, 27
	s_add_u32 s4, s4, s8
	s_addc_u32 s5, s5, 0
	s_lshl_b32 s8, s0, 26
	s_add_u32 s6, s6, s8
	s_addc_u32 s7, s7, 0
	s_lshl_b32 s30, s3, 14
	v_and_b32_e32 v120, 31, v200
	v_lshlrev_b32_e32 v2, 2, v120
	v_lshrrev_b32_e32 v3, 5, v200
	v_and_b32_e32 v4, 7, v200
	v_lshrrev_b32_e32 v6, 3, v200
	v_mul_u32_u24_e32 v7, 33, v3
	v_add_u32_e32 v7, v7, v120
	v_lshl_add_u32 v7, v7, 2, s30
	v_add_u32_e32 v8, 0x400, v7
	v_add_u32_e32 v9, 0x840, v7
	v_add_u32_e32 v10, 0xc40, v7
	v_add_u32_e32 v11, 0x1080, v7
	v_add_u32_e32 v12, 0x1480, v7
	v_add_u32_e32 v13, 0x18c0, v7
	v_add_u32_e32 v14, 0x1cc0, v7
	v_mul_u32_u24_e32 v120, 0x108, v4
	v_add_u32_e32 v120, v120, v6
	v_lshl_add_u32 v15, v120, 2, s30
	v_lshl_add_u32 v122, v3, 12, v2
	v_mov_b32_e32 v123, 0
	v_lshlrev_b32_e32 v124, 4, v4
	v_lshl_add_u32 v124, v6, 12, v124
	v_mov_b32_e32 v125, 0
	s_mov_b64 s[40:41], 0x10000
	s_mov_b64 s[42:43], 0x8000
	s_mov_b64 s[44:45], 0x2000
; #define WAVE_LDS_SYNC() do { int _z = 0; (void)emu::wave_xchg(&_z, 4); } while (0)
; #define LAS __attribute__((address_space(3)))
; #define WAVE_LDS_SYNC() asm volatile("s_waitcnt lgkmcnt(0)" ::: "memory")
; #define NT_LOAD(p) __builtin_nontemporal_load(p)
; #define NT_STORE(v, p) __builtin_nontemporal_store((v), (p))
; DEV unsigned pk2(float lo, float hi) { return f2bf(lo) | (f2bf(hi) << 16); }
; DEV unsigned pk2(float lo, float hi) { const f32x2n_t v = {lo, hi}; return __builtin_bit_cast(unsigned, __builtin_convertvector(v, bf16x2n_t)); }
; DEV void tr_item(const float* W, int ldw, int col0, int k0, bf16_t* WT, int K, int row0, LAS float* scr, int lane) {
; #pragma unroll 8
;     for (int i = 0; i < 32; ++i) { const int kk = 2 * i + (lane >> 5); scr[kk * 33 + (lane & 31)] = NT_LOAD(&W[(size_t)(k0 + kk) * ldw + col0 + (lane & 31)]); }
;     WAVE_LDS_SYNC();
;     const int c = lane & 7;
; #pragma unroll
;     for (int j = 0; j < 4; ++j) { const int n = (lane >> 3) + 8 * j; const LAS float* s = scr + (8 * c) * 33 + n;
;         u32x4 o; o.x = pk2(s[0 * 33], s[1 * 33]); o.y = pk2(s[2 * 33], s[3 * 33]); o.z = pk2(s[4 * 33], s[5 * 33]); o.w = pk2(s[6 * 33], s[7 * 33]);
;         NT_STORE(o, (u32x4*)(WT + (size_t)(row0 + n) * K + k0 + 8 * c)); }
; DEV void phase_prologue_a(const Frame& F0) {
;     ...
;         constexpr int D_ITEMS = (FF / 64) * 32;
;         for (int it = F.gw; it < NE * D_ITEMS; it += F.NGW) { const int e = it / D_ITEMS, r = it % D_ITEMS, kb = r / 32, nb = r % 32;
;             tr_item(GIN(I_WDOWN) + ((size_t)l * NE + e) * FF * 1024, 1024, 32 * nb, 64 * kb, (bf16_t*)(F.ws + WS_WD) + ((size_t)l * NE + e) * 1024 * FF, FF, 32 * nb, scr, F.lane); }
.Lsd_loop:
	s_lshr_b32 s8, s2, 10
	s_and_b32 s9, s2, 0x3ff
	s_lshr_b32 s10, s9, 5
	s_and_b32 s9, s9, 31
	s_lshl_b32 s24, s10, 18
	s_lshl_b32 s25, s9, 7
	s_add_i32 s24, s24, s25
	s_lshr_b32 s29, s8, 9
	s_lshl_b32 s28, s8, 23
	s_add_u32 s28, s28, s24
	s_addc_u32 s29, s29, 0
	s_add_u32 s28, s28, s4
	s_addc_u32 s29, s29, s5
	s_lshl_b32 s24, s9, 17
	s_lshl_b32 s25, s10, 7
	s_add_i32 s24, s24, s25
	s_lshr_b32 s11, s8, 10
	s_lshl_b32 s10, s8, 22
	s_add_u32 s10, s10, s24
	s_addc_u32 s11, s11, 0
	s_add_u32 s10, s10, s6
	s_addc_u32 s11, s11, s7
	v_lshl_add_u64 v[16:17], s[28:29], 0, v[122:123]
	v_lshl_add_u64 v[18:19], v[16:17], 0, s[44:45]
	v_lshl_add_u64 v[20:21], v[18:19], 0, s[44:45]
	v_lshl_add_u64 v[22:23], v[20:21], 0, s[44:45]
	v_lshl_add_u64 v[24:25], v[22:23], 0, s[44:45]
	v_lshl_add_u64 v[26:27], v[24:25], 0, s[44:45]
	v_lshl_add_u64 v[28:29], v[26:27], 0, s[44:45]
	v_lshl_add_u64 v[30:31], v[28:29], 0, s[44:45]
	global_load_dword v32, v[16:17], off nt
	global_load_dword v33, v[18:19], off nt
	global_load_dword v34, v[20:21], off nt
	global_load_dword v35, v[22:23], off nt
	global_load_dword v36, v[24:25], off nt
	global_load_dword v37, v[26:27], off nt
	global_load_dword v38, v[28:29], off nt
	global_load_dword v39, v[30:31], off nt
	v_lshl_add_u64 v[16:17], v[16:17], 0, s[40:41]
	v_lshl_add_u64 v[18:19], v[18:19], 0, s[40:41]
	v_lshl_add_u64 v[20:21], v[20:21], 0, s[40:41]
	v_lshl_add_u64 v[22:23], v[22:23], 0, s[40:41]
	v_lshl_add_u64 v[24:25], v[24:25], 0, s[40:41]
	v_lshl_add_u64 v[26:27], v[26:27], 0, s[40:41]
	v_lshl_add_u64 v[28:29], v[28:29], 0, s[40:41]
	v_lshl_add_u64 v[30:31], v[30:31], 0, s[40:41]
	global_load_dword v40, v[16:17], off nt
	global_load_dword v41, v[18:19], off nt
	global_load_dword v42, v[20:21], off nt
	global_load_dword v43, v[22:23], off nt
	global_load_dword v44, v[24:25], off nt
	global_load_dword v45, v[26:27], off nt
	global_load_dword v46, v[28:29], off nt
	global_load_dword v47, v[30:31], off nt
	v_lshl_add_u64 v[16:17], v[16:17], 0, s[40:41]
	v_lshl_add_u64 v[18:19], v[18:19], 0, s[40:41]
	v_lshl_add_u64 v[20:21], v[20:21], 0, s[40:41]
	v_lshl_add_u64 v[22:23], v[22:23], 0, s[40:41]
	v_lshl_add_u64 v[24:25], v[24:25], 0, s[40:41]
	v_lshl_add_u64 v[26:27], v[26:27], 0, s[40:41]
	v_lshl_add_u64 v[28:29], v[28:29], 0, s[40:41]
	v_lshl_add_u64 v[30:31], v[30:31], 0, s[40:41]
	global_load_dword v48, v[16:17], off nt
	global_load_dword v49, v[18:19], off nt
	global_load_dword v50, v[20:21], off nt
	global_load_dword v51, v[22:23], off nt
	global_load_dword v52, v[24:25], off nt
	global_load_dword v53, v[26:27], off nt
	global_load_dword v54, v[28:29], off nt
	global_load_dword v55, v[30:31], off nt
	v_lshl_add_u64 v[16:17], v[16:17], 0, s[40:41]
	v_lshl_add_u64 v[18:19], v[18:19], 0, s[40:41]
	v_lshl_add_u64 v[20:21], v[20:21], 0, s[40:41]
	v_lshl_add_u64 v[22:23], v[22:23], 0, s[40:41]
	v_lshl_add_u64 v[24:25], v[24:25], 0, s[40:41]
	v_lshl_add_u64 v[26:27], v[26:27], 0, s[40:41]
	v_lshl_add_u64 v[28:29], v[28:29], 0, s[40:41]
	v_lshl_add_u64 v[30:31], v[30:31], 0, s[40:41]
	global_load_dword v56, v[16:17], off nt
	global_load_dword v57, v[18:19], off nt
	global_load_dword v58, v[20:21], off nt
	global_load_dword v59, v[22:23], off nt
	global_load_dword v60, v[24:25], off nt
	global_load_dword v61, v[26:27], off nt
	global_load_dword v62, v[28:29], off nt
	global_load_dword v63, v[30:31], off nt
	v_lshl_add_u64 v[64:65], s[10:11], 0, v[124:125]
	v_lshl_add_u64 v[66:67], v[64:65], 0, s[42:43]
	v_lshl_add_u64 v[68:69], v[66:67], 0, s[42:43]
	v_lshl_add_u64 v[70:71], v[68:69], 0, s[42:43]
	s_waitcnt vmcnt(30)
	ds_write2_b32 v7, v32, v33 offset1:66
	s_waitcnt vmcnt(28)
	ds_write2_b32 v7, v34, v35 offset0:132 offset1:198
	s_waitcnt vmcnt(26)
	ds_write2_b32 v8, v36, v37 offset0:8 offset1:74
	s_waitcnt vmcnt(24)
	ds_write2_b32 v8, v38, v39 offset0:140 offset1:206
	s_waitcnt vmcnt(22)
	ds_write2_b32 v9, v40, v41 offset1:66
	s_waitcnt vmcnt(20)
	ds_write2_b32 v9, v42, v43 offset0:132 offset1:198
	s_waitcnt vmcnt(18)
	ds_write2_b32 v10, v44, v45 offset0:8 offset1:74
	s_waitcnt vmcnt(16)
	ds_write2_b32 v10, v46, v47 offset0:140 offset1:206
	s_waitcnt vmcnt(14)
	ds_write2_b32 v11, v48, v49 offset1:66
	s_waitcnt vmcnt(12)
	ds_write2_b32 v11, v50, v51 offset0:132 offset1:198
	s_waitcnt vmcnt(10)
	ds_write2_b32 v12, v52, v53 offset0:8 offset1:74
	s_waitcnt vmcnt(8)
	ds_write2_b32 v12, v54, v55 offset0:140 offset1:206
	s_waitcnt vmcnt(6)
	ds_write2_b32 v13, v56, v57 offset1:66
	s_waitcnt vmcnt(4)
	ds_write2_b32 v13, v58, v59 offset0:132 offset1:198
	s_waitcnt vmcnt(2)
	ds_write2_b32 v14, v60, v61 offset0:8 offset1:74
	s_waitcnt vmcnt(0)
	ds_write2_b32 v14, v62, v63 offset0:140 offset1:206
	ds_read2_b32 v[72:73], v15 offset1:8
	ds_read2_b32 v[74:75], v15 offset0:33 offset1:41
	ds_read2_b32 v[76:77], v15 offset0:66 offset1:74
	ds_read2_b32 v[78:79], v15 offset0:99 offset1:107
	ds_read2_b32 v[80:81], v15 offset0:132 offset1:140
	ds_read2_b32 v[82:83], v15 offset0:165 offset1:173
	ds_read2_b32 v[84:85], v15 offset0:198 offset1:206
	ds_read2_b32 v[86:87], v15 offset0:231 offset1:239
	ds_read2_b32 v[88:89], v15 offset0:16 offset1:24
	ds_read2_b32 v[90:91], v15 offset0:49 offset1:57
	ds_read2_b32 v[92:93], v15 offset0:82 offset1:90
	ds_read2_b32 v[94:95], v15 offset0:115 offset1:123
	s_waitcnt lgkmcnt(4)
	v_cvt_pk_bf16_f32 v104, v72, v74
	v_cvt_pk_bf16_f32 v105, v76, v78
	v_cvt_pk_bf16_f32 v106, v80, v82
	v_cvt_pk_bf16_f32 v107, v84, v86
	v_cvt_pk_bf16_f32 v108, v73, v75
	v_cvt_pk_bf16_f32 v109, v77, v79
	v_cvt_pk_bf16_f32 v110, v81, v83
	v_cvt_pk_bf16_f32 v111, v85, v87
	ds_read2_b32 v[96:97], v15 offset0:148 offset1:156
	ds_read2_b32 v[98:99], v15 offset0:181 offset1:189
	ds_read2_b32 v[100:101], v15 offset0:214 offset1:222
	ds_read2_b32 v[102:103], v15 offset0:247 offset1:255
	global_store_dwordx4 v[64:65], v[104:107], off nt
	global_store_dwordx4 v[66:67], v[108:111], off nt
	s_waitcnt lgkmcnt(0)
	v_cvt_pk_bf16_f32 v112, v88, v90
	v_cvt_pk_bf16_f32 v113, v92, v94
	v_cvt_pk_bf16_f32 v114, v96, v98
	v_cvt_pk_bf16_f32 v115, v100, v102
	v_cvt_pk_bf16_f32 v116, v89, v91
	v_cvt_pk_bf16_f32 v117, v93, v95
	v_cvt_pk_bf16_f32 v118, v97, v99
	v_cvt_pk_bf16_f32 v119, v101, v103
	global_store_dwordx4 v[68:69], v[112:115], off nt
	global_store_dwordx4 v[70:71], v[116:119], off nt
	s_addk_i32 s2, 0x200
	s_cmp_lt_u32 s2, 0x4000
	s_cbranch_scc1 .Lsd_loop
